# scan recurrence: two chunks per loop iteration with LDS lane addresses formed once, value scalar of two steps per ds_read2st64, first step of a chunk starts on its first operand (counted waits)
# speedup vs baseline: 1.0292x; 1.0096x over previous
.LBB0_1044:
	v_readlane_b32 s0, v255, 40
	v_readlane_b32 s1, v255, 41
	s_andn2_b64 vcc, exec, s[0:1]
	s_cbranch_vccnz .LBB0_1103
	s_and_b32 s6, s2, 3
	v_readlane_b32 s7, v255, 0
	s_mov_b64 s[0:1], -1
	s_cmpk_lt_u32 s7, 0x100
	v_lshlrev_b32_e32 v22, 3, v169
	s_cbranch_scc0 .LBB0_1049
	v_readlane_b32 s1, v255, 5
	s_lshl_b32 s0, s6, 4
	s_lshl_b32 s1, s1, 2
	s_or_b32 s0, s1, s0
	v_or_b32_e32 v6, s0, v166
	s_setprio 3
	v_or_b32_e32 v2, s1, v166
	s_movk_i32 s0, 0x90
	v_mul_lo_u32 v2, v2, s0
	v_add3_u32 v7, 0, v2, v22
	v_mov_b32_e32 v2, 0
	s_mov_b32 s0, 0
	v_mov_b32_e32 v3, v2
	v_mov_b32_e32 v4, v2
	v_mov_b32_e32 v5, v2
	v_lshlrev_b32_e32 v9, 4, v169
	v_lshlrev_b32_e32 v10, 2, v6
	v_mov_b32_e32 v11, v7
	v_add_u32_e32 v8, 0xb000, v7
	v_add_u32_e32 v114, 0x5000, v9
	v_add_u32_e32 v115, 0x5000, v10
	v_add_u32_e32 v116, 0x9000, v7
	v_add_u32_e32 v117, 0x9000, v8
	s_barrier
.LBB0_1047:
	ds_read_b128 v[44:47], v9 offset:256
	ds_read_b128 v[40:43], v9
	ds_read_b128 v[52:55], v9 offset:768
	ds_read2st64_b32 v[56:57], v10 offset0:4 offset1:9
	ds_read_b128 v[48:51], v9 offset:512
	ds_read_b128 v[80:83], v9 offset:1536
	ds_read_b128 v[76:79], v9 offset:1280
	ds_read_b128 v[88:91], v9 offset:2048
	ds_read_b128 v[84:87], v9 offset:1792
	s_waitcnt lgkmcnt(8)
	v_pk_mul_f32 v[58:59], v[44:45], v[2:3]
	s_waitcnt lgkmcnt(7)
	v_pk_mul_f32 v[60:61], v[40:41], v[2:3]
	v_pk_fma_f32 v[58:59], v[46:47], v[4:5], v[58:59]
	v_pk_mul_f32 v[62:63], v[42:43], v[4:5]
	v_add_f32_e32 v64, v58, v59
	s_waitcnt lgkmcnt(5)
	v_pk_fma_f32 v[60:61], v[52:53], v[56:57], v[60:61] op_sel_hi:[1,0,1]
	v_pk_fma_f32 v[62:63], v[54:55], v[56:57], v[62:63] op_sel_hi:[1,0,1]
	v_add_f32_dpp v65, v64, v64 quad_perm:[1,0,3,2] row_mask:0xf bank_mask:0xf bound_ctrl:1
	ds_read_b128 v[100:103], v9 offset:2816
	ds_read_b128 v[96:99], v9 offset:2560
	v_add_f32_dpp v64, v65, v65 quad_perm:[2,3,0,1] row_mask:0xf bank_mask:0xf bound_ctrl:1
	ds_read_b128 v[108:111], v9 offset:3328
	ds_read2st64_b32 v[92:93], v10 offset0:14 offset1:19
	v_add_f32_dpp v65, v64, v64 row_half_mirror row_mask:0xf bank_mask:0xf bound_ctrl:1
	ds_read_b128 v[104:107], v9 offset:3072
	s_nop 0
	v_add_f32_dpp v66, v65, v65 row_mirror row_mask:0xf bank_mask:0xf bound_ctrl:1
	s_waitcnt lgkmcnt(9)
	v_pk_fma_f32 v[2:3], v[48:49], v[66:67], v[60:61] op_sel_hi:[1,0,1]
	v_pk_fma_f32 v[4:5], v[50:51], v[66:67], v[62:63] op_sel_hi:[1,0,1]
	s_waitcnt lgkmcnt(5)
	v_pk_mul_f32 v[58:59], v[80:81], v[2:3]
	v_pk_mul_f32 v[60:61], v[76:77], v[2:3]
	v_pk_fma_f32 v[58:59], v[82:83], v[4:5], v[58:59]
	v_pk_mul_f32 v[62:63], v[78:79], v[4:5]
	v_add_f32_e32 v64, v58, v59
	v_pk_fma_f32 v[60:61], v[88:89], v[56:57], v[60:61] op_sel:[0,1,0]
	v_pk_fma_f32 v[62:63], v[90:91], v[56:57], v[62:63] op_sel:[0,1,0]
	v_add_f32_dpp v65, v64, v64 quad_perm:[1,0,3,2] row_mask:0xf bank_mask:0xf bound_ctrl:1
	v_cvt_pk_bf16_f32 v68, v2, v3
	v_cvt_pk_bf16_f32 v69, v4, v5
	v_add_f32_dpp v64, v65, v65 quad_perm:[2,3,0,1] row_mask:0xf bank_mask:0xf bound_ctrl:1
	ds_write_b64 v11, v[68:69] offset:45056
	ds_read_b128 v[44:47], v9 offset:4096
	v_add_f32_dpp v65, v64, v64 row_half_mirror row_mask:0xf bank_mask:0xf bound_ctrl:1
	ds_read_b128 v[40:43], v9 offset:3840
	ds_read_b128 v[52:55], v9 offset:4608
	v_add_f32_dpp v66, v65, v65 row_mirror row_mask:0xf bank_mask:0xf bound_ctrl:1
	v_pk_fma_f32 v[2:3], v[84:85], v[66:67], v[60:61] op_sel_hi:[1,0,1]
	v_pk_fma_f32 v[4:5], v[86:87], v[66:67], v[62:63] op_sel_hi:[1,0,1]
	ds_read_b128 v[48:51], v9 offset:4352
	s_waitcnt lgkmcnt(5)
	v_pk_mul_f32 v[58:59], v[100:101], v[2:3]
	v_pk_mul_f32 v[60:61], v[96:97], v[2:3]
	v_pk_fma_f32 v[58:59], v[102:103], v[4:5], v[58:59]
	v_pk_mul_f32 v[62:63], v[98:99], v[4:5]
	v_add_f32_e32 v64, v58, v59
	v_pk_fma_f32 v[60:61], v[108:109], v[92:93], v[60:61] op_sel_hi:[1,0,1]
	v_pk_fma_f32 v[62:63], v[110:111], v[92:93], v[62:63] op_sel_hi:[1,0,1]
	v_add_f32_dpp v65, v64, v64 quad_perm:[1,0,3,2] row_mask:0xf bank_mask:0xf bound_ctrl:1
	v_cvt_pk_bf16_f32 v70, v2, v3
	v_cvt_pk_bf16_f32 v71, v4, v5
	v_add_f32_dpp v64, v65, v65 quad_perm:[2,3,0,1] row_mask:0xf bank_mask:0xf bound_ctrl:1
	ds_write_b64 v11, v[70:71] offset:47360
	ds_read_b128 v[80:83], v9 offset:5376
	v_add_f32_dpp v65, v64, v64 row_half_mirror row_mask:0xf bank_mask:0xf bound_ctrl:1
	ds_read_b128 v[76:79], v9 offset:5120
	ds_read_b128 v[88:91], v9 offset:5888
	v_add_f32_dpp v66, v65, v65 row_mirror row_mask:0xf bank_mask:0xf bound_ctrl:1
	v_pk_fma_f32 v[2:3], v[104:105], v[66:67], v[60:61] op_sel_hi:[1,0,1]
	v_pk_fma_f32 v[4:5], v[106:107], v[66:67], v[62:63] op_sel_hi:[1,0,1]
	ds_read2st64_b32 v[56:57], v10 offset0:24 offset1:29
	ds_read_b128 v[84:87], v9 offset:5632
	s_waitcnt lgkmcnt(6)
	v_pk_mul_f32 v[58:59], v[44:45], v[2:3]
	v_pk_mul_f32 v[60:61], v[40:41], v[2:3]
	v_pk_fma_f32 v[58:59], v[46:47], v[4:5], v[58:59]
	v_pk_mul_f32 v[62:63], v[42:43], v[4:5]
	v_add_f32_e32 v64, v58, v59
	v_pk_fma_f32 v[60:61], v[52:53], v[92:93], v[60:61] op_sel:[0,1,0]
	v_pk_fma_f32 v[62:63], v[54:55], v[92:93], v[62:63] op_sel:[0,1,0]
	v_add_f32_dpp v65, v64, v64 quad_perm:[1,0,3,2] row_mask:0xf bank_mask:0xf bound_ctrl:1
	v_cvt_pk_bf16_f32 v68, v2, v3
	v_cvt_pk_bf16_f32 v69, v4, v5
	v_add_f32_dpp v64, v65, v65 quad_perm:[2,3,0,1] row_mask:0xf bank_mask:0xf bound_ctrl:1
	ds_write_b64 v11, v[68:69] offset:49664
	ds_read_b128 v[100:103], v9 offset:6656
	v_add_f32_dpp v65, v64, v64 row_half_mirror row_mask:0xf bank_mask:0xf bound_ctrl:1
	ds_read_b128 v[96:99], v9 offset:6400
	ds_read_b128 v[108:111], v9 offset:7168
	v_add_f32_dpp v66, v65, v65 row_mirror row_mask:0xf bank_mask:0xf bound_ctrl:1
	v_pk_fma_f32 v[2:3], v[48:49], v[66:67], v[60:61] op_sel_hi:[1,0,1]
	v_pk_fma_f32 v[4:5], v[50:51], v[66:67], v[62:63] op_sel_hi:[1,0,1]
	ds_read_b128 v[104:107], v9 offset:6912
	s_waitcnt lgkmcnt(5)
	v_pk_mul_f32 v[58:59], v[80:81], v[2:3]
	v_pk_mul_f32 v[60:61], v[76:77], v[2:3]
	v_pk_fma_f32 v[58:59], v[82:83], v[4:5], v[58:59]
	v_pk_mul_f32 v[62:63], v[78:79], v[4:5]
	v_add_f32_e32 v64, v58, v59
	v_pk_fma_f32 v[60:61], v[88:89], v[56:57], v[60:61] op_sel_hi:[1,0,1]
	v_pk_fma_f32 v[62:63], v[90:91], v[56:57], v[62:63] op_sel_hi:[1,0,1]
	v_add_f32_dpp v65, v64, v64 quad_perm:[1,0,3,2] row_mask:0xf bank_mask:0xf bound_ctrl:1
	v_cvt_pk_bf16_f32 v70, v2, v3
	v_cvt_pk_bf16_f32 v71, v4, v5
	v_add_f32_dpp v64, v65, v65 quad_perm:[2,3,0,1] row_mask:0xf bank_mask:0xf bound_ctrl:1
	ds_write_b64 v11, v[70:71] offset:51968
	ds_read_b128 v[44:47], v9 offset:7936
	v_add_f32_dpp v65, v64, v64 row_half_mirror row_mask:0xf bank_mask:0xf bound_ctrl:1
	ds_read_b128 v[40:43], v9 offset:7680
	ds_read_b128 v[52:55], v9 offset:8448
	v_add_f32_dpp v66, v65, v65 row_mirror row_mask:0xf bank_mask:0xf bound_ctrl:1
	v_pk_fma_f32 v[2:3], v[84:85], v[66:67], v[60:61] op_sel_hi:[1,0,1]
	v_pk_fma_f32 v[4:5], v[86:87], v[66:67], v[62:63] op_sel_hi:[1,0,1]
	ds_read2st64_b32 v[92:93], v10 offset0:34 offset1:39
	ds_read_b128 v[48:51], v9 offset:8192
	s_waitcnt lgkmcnt(6)
	v_pk_mul_f32 v[58:59], v[100:101], v[2:3]
	v_pk_mul_f32 v[60:61], v[96:97], v[2:3]
	v_pk_fma_f32 v[58:59], v[102:103], v[4:5], v[58:59]
	v_pk_mul_f32 v[62:63], v[98:99], v[4:5]
	v_add_f32_e32 v64, v58, v59
	v_pk_fma_f32 v[60:61], v[108:109], v[56:57], v[60:61] op_sel:[0,1,0]
	v_pk_fma_f32 v[62:63], v[110:111], v[56:57], v[62:63] op_sel:[0,1,0]
	v_add_f32_dpp v65, v64, v64 quad_perm:[1,0,3,2] row_mask:0xf bank_mask:0xf bound_ctrl:1
	v_cvt_pk_bf16_f32 v68, v2, v3
	v_cvt_pk_bf16_f32 v69, v4, v5
	v_add_f32_dpp v64, v65, v65 quad_perm:[2,3,0,1] row_mask:0xf bank_mask:0xf bound_ctrl:1
	ds_write_b64 v11, v[68:69] offset:54272
	ds_read_b128 v[80:83], v9 offset:9216
	v_add_f32_dpp v65, v64, v64 row_half_mirror row_mask:0xf bank_mask:0xf bound_ctrl:1
	ds_read_b128 v[76:79], v9 offset:8960
	ds_read_b128 v[88:91], v9 offset:9728
	v_add_f32_dpp v66, v65, v65 row_mirror row_mask:0xf bank_mask:0xf bound_ctrl:1
	v_pk_fma_f32 v[2:3], v[104:105], v[66:67], v[60:61] op_sel_hi:[1,0,1]
	v_pk_fma_f32 v[4:5], v[106:107], v[66:67], v[62:63] op_sel_hi:[1,0,1]
	ds_read_b128 v[84:87], v9 offset:9472
	s_waitcnt lgkmcnt(5)
	v_pk_mul_f32 v[58:59], v[44:45], v[2:3]
	v_pk_mul_f32 v[60:61], v[40:41], v[2:3]
	v_pk_fma_f32 v[58:59], v[46:47], v[4:5], v[58:59]
	v_pk_mul_f32 v[62:63], v[42:43], v[4:5]
	v_add_f32_e32 v64, v58, v59
	v_pk_fma_f32 v[60:61], v[52:53], v[92:93], v[60:61] op_sel_hi:[1,0,1]
	v_pk_fma_f32 v[62:63], v[54:55], v[92:93], v[62:63] op_sel_hi:[1,0,1]
	v_add_f32_dpp v65, v64, v64 quad_perm:[1,0,3,2] row_mask:0xf bank_mask:0xf bound_ctrl:1
	v_cvt_pk_bf16_f32 v70, v2, v3
	v_cvt_pk_bf16_f32 v71, v4, v5
	v_add_f32_dpp v64, v65, v65 quad_perm:[2,3,0,1] row_mask:0xf bank_mask:0xf bound_ctrl:1
	ds_write_b64 v11, v[70:71] offset:56576
	ds_read_b128 v[100:103], v9 offset:10496
	v_add_f32_dpp v65, v64, v64 row_half_mirror row_mask:0xf bank_mask:0xf bound_ctrl:1
	ds_read_b128 v[96:99], v9 offset:10240
	ds_read_b128 v[108:111], v9 offset:11008
	v_add_f32_dpp v66, v65, v65 row_mirror row_mask:0xf bank_mask:0xf bound_ctrl:1
	v_pk_fma_f32 v[2:3], v[48:49], v[66:67], v[60:61] op_sel_hi:[1,0,1]
	v_pk_fma_f32 v[4:5], v[50:51], v[66:67], v[62:63] op_sel_hi:[1,0,1]
	ds_read2st64_b32 v[56:57], v10 offset0:44 offset1:49
	ds_read_b128 v[104:107], v9 offset:10752
	s_waitcnt lgkmcnt(6)
	v_pk_mul_f32 v[58:59], v[80:81], v[2:3]
	v_pk_mul_f32 v[60:61], v[76:77], v[2:3]
	v_pk_fma_f32 v[58:59], v[82:83], v[4:5], v[58:59]
	v_pk_mul_f32 v[62:63], v[78:79], v[4:5]
	v_add_f32_e32 v64, v58, v59
	v_pk_fma_f32 v[60:61], v[88:89], v[92:93], v[60:61] op_sel:[0,1,0]
	v_pk_fma_f32 v[62:63], v[90:91], v[92:93], v[62:63] op_sel:[0,1,0]
	v_add_f32_dpp v65, v64, v64 quad_perm:[1,0,3,2] row_mask:0xf bank_mask:0xf bound_ctrl:1
	v_cvt_pk_bf16_f32 v68, v2, v3
	v_cvt_pk_bf16_f32 v69, v4, v5
	v_add_f32_dpp v64, v65, v65 quad_perm:[2,3,0,1] row_mask:0xf bank_mask:0xf bound_ctrl:1
	ds_write_b64 v11, v[68:69] offset:58880
	ds_read_b128 v[44:47], v9 offset:11776
	v_add_f32_dpp v65, v64, v64 row_half_mirror row_mask:0xf bank_mask:0xf bound_ctrl:1
	ds_read_b128 v[40:43], v9 offset:11520
	ds_read_b128 v[52:55], v9 offset:12288
	v_add_f32_dpp v66, v65, v65 row_mirror row_mask:0xf bank_mask:0xf bound_ctrl:1
	v_pk_fma_f32 v[2:3], v[84:85], v[66:67], v[60:61] op_sel_hi:[1,0,1]
	v_pk_fma_f32 v[4:5], v[86:87], v[66:67], v[62:63] op_sel_hi:[1,0,1]
	ds_read_b128 v[48:51], v9 offset:12032
	s_waitcnt lgkmcnt(5)
	v_pk_mul_f32 v[58:59], v[100:101], v[2:3]
	v_pk_mul_f32 v[60:61], v[96:97], v[2:3]
	v_pk_fma_f32 v[58:59], v[102:103], v[4:5], v[58:59]
	v_pk_mul_f32 v[62:63], v[98:99], v[4:5]
	v_add_f32_e32 v64, v58, v59
	v_pk_fma_f32 v[60:61], v[108:109], v[56:57], v[60:61] op_sel_hi:[1,0,1]
	v_pk_fma_f32 v[62:63], v[110:111], v[56:57], v[62:63] op_sel_hi:[1,0,1]
	v_add_f32_dpp v65, v64, v64 quad_perm:[1,0,3,2] row_mask:0xf bank_mask:0xf bound_ctrl:1
	v_cvt_pk_bf16_f32 v70, v2, v3
	v_cvt_pk_bf16_f32 v71, v4, v5
	v_add_f32_dpp v64, v65, v65 quad_perm:[2,3,0,1] row_mask:0xf bank_mask:0xf bound_ctrl:1
	ds_write_b64 v11, v[70:71] offset:61184
	ds_read_b128 v[80:83], v9 offset:13056
	v_add_f32_dpp v65, v64, v64 row_half_mirror row_mask:0xf bank_mask:0xf bound_ctrl:1
	ds_read_b128 v[76:79], v9 offset:12800
	ds_read_b128 v[88:91], v9 offset:13568
	v_add_f32_dpp v66, v65, v65 row_mirror row_mask:0xf bank_mask:0xf bound_ctrl:1
	v_pk_fma_f32 v[2:3], v[104:105], v[66:67], v[60:61] op_sel_hi:[1,0,1]
	v_pk_fma_f32 v[4:5], v[106:107], v[66:67], v[62:63] op_sel_hi:[1,0,1]
	ds_read2st64_b32 v[92:93], v10 offset0:54 offset1:59
	ds_read_b128 v[84:87], v9 offset:13312
	s_waitcnt lgkmcnt(6)
	v_pk_mul_f32 v[58:59], v[44:45], v[2:3]
	v_pk_mul_f32 v[60:61], v[40:41], v[2:3]
	v_pk_fma_f32 v[58:59], v[46:47], v[4:5], v[58:59]
	v_pk_mul_f32 v[62:63], v[42:43], v[4:5]
	v_add_f32_e32 v64, v58, v59
	v_pk_fma_f32 v[60:61], v[52:53], v[56:57], v[60:61] op_sel:[0,1,0]
	v_pk_fma_f32 v[62:63], v[54:55], v[56:57], v[62:63] op_sel:[0,1,0]
	v_add_f32_dpp v65, v64, v64 quad_perm:[1,0,3,2] row_mask:0xf bank_mask:0xf bound_ctrl:1
	v_cvt_pk_bf16_f32 v68, v2, v3
	v_cvt_pk_bf16_f32 v69, v4, v5
	v_add_f32_dpp v64, v65, v65 quad_perm:[2,3,0,1] row_mask:0xf bank_mask:0xf bound_ctrl:1
	ds_write_b64 v11, v[68:69] offset:63488
	ds_read_b128 v[100:103], v9 offset:14336
	v_add_f32_dpp v65, v64, v64 row_half_mirror row_mask:0xf bank_mask:0xf bound_ctrl:1
	ds_read_b128 v[96:99], v9 offset:14080
	ds_read_b128 v[108:111], v9 offset:14848
	v_add_f32_dpp v66, v65, v65 row_mirror row_mask:0xf bank_mask:0xf bound_ctrl:1
	v_pk_fma_f32 v[2:3], v[48:49], v[66:67], v[60:61] op_sel_hi:[1,0,1]
	v_pk_fma_f32 v[4:5], v[50:51], v[66:67], v[62:63] op_sel_hi:[1,0,1]
	ds_read_b128 v[104:107], v9 offset:14592
	s_waitcnt lgkmcnt(5)
	v_pk_mul_f32 v[58:59], v[80:81], v[2:3]
	v_pk_mul_f32 v[60:61], v[76:77], v[2:3]
	v_pk_fma_f32 v[58:59], v[82:83], v[4:5], v[58:59]
	v_pk_mul_f32 v[62:63], v[78:79], v[4:5]
	v_add_f32_e32 v64, v58, v59
	v_pk_fma_f32 v[60:61], v[88:89], v[92:93], v[60:61] op_sel_hi:[1,0,1]
	v_pk_fma_f32 v[62:63], v[90:91], v[92:93], v[62:63] op_sel_hi:[1,0,1]
	v_add_f32_dpp v65, v64, v64 quad_perm:[1,0,3,2] row_mask:0xf bank_mask:0xf bound_ctrl:1
	v_cvt_pk_bf16_f32 v70, v2, v3
	v_cvt_pk_bf16_f32 v71, v4, v5
	v_add_f32_dpp v64, v65, v65 quad_perm:[2,3,0,1] row_mask:0xf bank_mask:0xf bound_ctrl:1
	ds_write_b64 v8, v[70:71] offset:20736
	ds_read_b128 v[44:47], v9 offset:15616
	v_add_f32_dpp v65, v64, v64 row_half_mirror row_mask:0xf bank_mask:0xf bound_ctrl:1
	ds_read_b128 v[40:43], v9 offset:15360
	ds_read_b128 v[52:55], v9 offset:16128
	v_add_f32_dpp v66, v65, v65 row_mirror row_mask:0xf bank_mask:0xf bound_ctrl:1
	v_pk_fma_f32 v[2:3], v[84:85], v[66:67], v[60:61] op_sel_hi:[1,0,1]
	v_pk_fma_f32 v[4:5], v[86:87], v[66:67], v[62:63] op_sel_hi:[1,0,1]
	ds_read2st64_b32 v[56:57], v10 offset0:64 offset1:69
	ds_read_b128 v[48:51], v9 offset:15872
	s_waitcnt lgkmcnt(6)
	v_pk_mul_f32 v[58:59], v[100:101], v[2:3]
	v_pk_mul_f32 v[60:61], v[96:97], v[2:3]
	v_pk_fma_f32 v[58:59], v[102:103], v[4:5], v[58:59]
	v_pk_mul_f32 v[62:63], v[98:99], v[4:5]
	v_add_f32_e32 v64, v58, v59
	v_pk_fma_f32 v[60:61], v[108:109], v[92:93], v[60:61] op_sel:[0,1,0]
	v_pk_fma_f32 v[62:63], v[110:111], v[92:93], v[62:63] op_sel:[0,1,0]
	v_add_f32_dpp v65, v64, v64 quad_perm:[1,0,3,2] row_mask:0xf bank_mask:0xf bound_ctrl:1
	v_cvt_pk_bf16_f32 v68, v2, v3
	v_cvt_pk_bf16_f32 v69, v4, v5
	v_add_f32_dpp v64, v65, v65 quad_perm:[2,3,0,1] row_mask:0xf bank_mask:0xf bound_ctrl:1
	ds_write_b64 v8, v[68:69] offset:23040
	ds_read_b128 v[80:83], v9 offset:16896
	v_add_f32_dpp v65, v64, v64 row_half_mirror row_mask:0xf bank_mask:0xf bound_ctrl:1
	ds_read_b128 v[76:79], v9 offset:16640
	ds_read_b128 v[88:91], v9 offset:17408
	v_add_f32_dpp v66, v65, v65 row_mirror row_mask:0xf bank_mask:0xf bound_ctrl:1
	v_pk_fma_f32 v[2:3], v[104:105], v[66:67], v[60:61] op_sel_hi:[1,0,1]
	v_pk_fma_f32 v[4:5], v[106:107], v[66:67], v[62:63] op_sel_hi:[1,0,1]
	ds_read_b128 v[84:87], v9 offset:17152
	s_waitcnt lgkmcnt(5)
	v_pk_mul_f32 v[58:59], v[44:45], v[2:3]
	v_pk_mul_f32 v[60:61], v[40:41], v[2:3]
	v_pk_fma_f32 v[58:59], v[46:47], v[4:5], v[58:59]
	v_pk_mul_f32 v[62:63], v[42:43], v[4:5]
	v_add_f32_e32 v64, v58, v59
	v_pk_fma_f32 v[60:61], v[52:53], v[56:57], v[60:61] op_sel_hi:[1,0,1]
	v_pk_fma_f32 v[62:63], v[54:55], v[56:57], v[62:63] op_sel_hi:[1,0,1]
	v_add_f32_dpp v65, v64, v64 quad_perm:[1,0,3,2] row_mask:0xf bank_mask:0xf bound_ctrl:1
	v_cvt_pk_bf16_f32 v70, v2, v3
	v_cvt_pk_bf16_f32 v71, v4, v5
	v_add_f32_dpp v64, v65, v65 quad_perm:[2,3,0,1] row_mask:0xf bank_mask:0xf bound_ctrl:1
	ds_write_b64 v8, v[70:71] offset:25344
	ds_read_b128 v[100:103], v9 offset:18176
	v_add_f32_dpp v65, v64, v64 row_half_mirror row_mask:0xf bank_mask:0xf bound_ctrl:1
	ds_read_b128 v[96:99], v9 offset:17920
	ds_read_b128 v[108:111], v9 offset:18688
	v_add_f32_dpp v66, v65, v65 row_mirror row_mask:0xf bank_mask:0xf bound_ctrl:1
	v_pk_fma_f32 v[2:3], v[48:49], v[66:67], v[60:61] op_sel_hi:[1,0,1]
	v_pk_fma_f32 v[4:5], v[50:51], v[66:67], v[62:63] op_sel_hi:[1,0,1]
	ds_read2st64_b32 v[92:93], v10 offset0:74 offset1:79
	ds_read_b128 v[104:107], v9 offset:18432
	s_waitcnt lgkmcnt(6)
	v_pk_mul_f32 v[58:59], v[80:81], v[2:3]
	v_pk_mul_f32 v[60:61], v[76:77], v[2:3]
	v_pk_fma_f32 v[58:59], v[82:83], v[4:5], v[58:59]
	v_pk_mul_f32 v[62:63], v[78:79], v[4:5]
	v_add_f32_e32 v64, v58, v59
	v_pk_fma_f32 v[60:61], v[88:89], v[56:57], v[60:61] op_sel:[0,1,0]
	v_pk_fma_f32 v[62:63], v[90:91], v[56:57], v[62:63] op_sel:[0,1,0]
	v_add_f32_dpp v65, v64, v64 quad_perm:[1,0,3,2] row_mask:0xf bank_mask:0xf bound_ctrl:1
	v_cvt_pk_bf16_f32 v68, v2, v3
	v_cvt_pk_bf16_f32 v69, v4, v5
	v_add_f32_dpp v64, v65, v65 quad_perm:[2,3,0,1] row_mask:0xf bank_mask:0xf bound_ctrl:1
	ds_write_b64 v8, v[68:69] offset:27648
	ds_read_b128 v[44:47], v9 offset:19456
	v_add_f32_dpp v65, v64, v64 row_half_mirror row_mask:0xf bank_mask:0xf bound_ctrl:1
	ds_read_b128 v[40:43], v9 offset:19200
	ds_read_b128 v[52:55], v9 offset:19968
	v_add_f32_dpp v66, v65, v65 row_mirror row_mask:0xf bank_mask:0xf bound_ctrl:1
	v_pk_fma_f32 v[2:3], v[84:85], v[66:67], v[60:61] op_sel_hi:[1,0,1]
	v_pk_fma_f32 v[4:5], v[86:87], v[66:67], v[62:63] op_sel_hi:[1,0,1]
	ds_read_b128 v[48:51], v9 offset:19712
	s_waitcnt lgkmcnt(5)
	v_pk_mul_f32 v[58:59], v[100:101], v[2:3]
	v_pk_mul_f32 v[60:61], v[96:97], v[2:3]
	v_pk_fma_f32 v[58:59], v[102:103], v[4:5], v[58:59]
	v_pk_mul_f32 v[62:63], v[98:99], v[4:5]
	v_add_f32_e32 v64, v58, v59
	v_pk_fma_f32 v[60:61], v[108:109], v[92:93], v[60:61] op_sel_hi:[1,0,1]
	v_pk_fma_f32 v[62:63], v[110:111], v[92:93], v[62:63] op_sel_hi:[1,0,1]
	v_add_f32_dpp v65, v64, v64 quad_perm:[1,0,3,2] row_mask:0xf bank_mask:0xf bound_ctrl:1
	v_cvt_pk_bf16_f32 v70, v2, v3
	v_cvt_pk_bf16_f32 v71, v4, v5
	v_add_f32_dpp v64, v65, v65 quad_perm:[2,3,0,1] row_mask:0xf bank_mask:0xf bound_ctrl:1
	ds_write_b64 v8, v[70:71] offset:29952
	s_nop 0
	v_add_f32_dpp v65, v64, v64 row_half_mirror row_mask:0xf bank_mask:0xf bound_ctrl:1
	s_nop 0
	s_nop 0
	v_add_f32_dpp v66, v65, v65 row_mirror row_mask:0xf bank_mask:0xf bound_ctrl:1
	v_pk_fma_f32 v[2:3], v[104:105], v[66:67], v[60:61] op_sel_hi:[1,0,1]
	v_pk_fma_f32 v[4:5], v[106:107], v[66:67], v[62:63] op_sel_hi:[1,0,1]
	s_waitcnt lgkmcnt(1)
	v_pk_mul_f32 v[58:59], v[44:45], v[2:3]
	v_pk_mul_f32 v[60:61], v[40:41], v[2:3]
	v_pk_fma_f32 v[58:59], v[46:47], v[4:5], v[58:59]
	v_pk_mul_f32 v[62:63], v[42:43], v[4:5]
	v_add_f32_e32 v64, v58, v59
	v_pk_fma_f32 v[60:61], v[52:53], v[92:93], v[60:61] op_sel:[0,1,0]
	v_pk_fma_f32 v[62:63], v[54:55], v[92:93], v[62:63] op_sel:[0,1,0]
	v_add_f32_dpp v65, v64, v64 quad_perm:[1,0,3,2] row_mask:0xf bank_mask:0xf bound_ctrl:1
	v_cvt_pk_bf16_f32 v68, v2, v3
	v_cvt_pk_bf16_f32 v69, v4, v5
	v_add_f32_dpp v64, v65, v65 quad_perm:[2,3,0,1] row_mask:0xf bank_mask:0xf bound_ctrl:1
	ds_write_b64 v8, v[68:69] offset:32256
	s_nop 0
	v_add_f32_dpp v65, v64, v64 row_half_mirror row_mask:0xf bank_mask:0xf bound_ctrl:1
	s_nop 0
	s_nop 0
	v_add_f32_dpp v66, v65, v65 row_mirror row_mask:0xf bank_mask:0xf bound_ctrl:1
	v_pk_fma_f32 v[2:3], v[48:49], v[66:67], v[60:61] op_sel_hi:[1,0,1]
	v_pk_fma_f32 v[4:5], v[50:51], v[66:67], v[62:63] op_sel_hi:[1,0,1]
	v_cvt_pk_bf16_f32 v70, v2, v3
	v_cvt_pk_bf16_f32 v71, v4, v5
	ds_write_b64 v8, v[70:71] offset:34560
	s_add_i32 s0, s0, 1
	s_cmpk_eq_i32 s0, 0x201
	s_waitcnt lgkmcnt(0)
	s_barrier
	s_cbranch_scc1 .Lscan_done
	ds_read_b128 v[44:47], v114 offset:256
	ds_read_b128 v[40:43], v114
	ds_read_b128 v[52:55], v114 offset:768
	ds_read2st64_b32 v[56:57], v115 offset0:4 offset1:9
	ds_read_b128 v[48:51], v114 offset:512
	ds_read_b128 v[80:83], v114 offset:1536
	ds_read_b128 v[76:79], v114 offset:1280
	ds_read_b128 v[88:91], v114 offset:2048
	ds_read_b128 v[84:87], v114 offset:1792
	s_waitcnt lgkmcnt(8)
	v_pk_mul_f32 v[58:59], v[44:45], v[2:3]
	s_waitcnt lgkmcnt(7)
	v_pk_mul_f32 v[60:61], v[40:41], v[2:3]
	v_pk_fma_f32 v[58:59], v[46:47], v[4:5], v[58:59]
	v_pk_mul_f32 v[62:63], v[42:43], v[4:5]
	v_add_f32_e32 v64, v58, v59
	s_waitcnt lgkmcnt(5)
	v_pk_fma_f32 v[60:61], v[52:53], v[56:57], v[60:61] op_sel_hi:[1,0,1]
	v_pk_fma_f32 v[62:63], v[54:55], v[56:57], v[62:63] op_sel_hi:[1,0,1]
	v_add_f32_dpp v65, v64, v64 quad_perm:[1,0,3,2] row_mask:0xf bank_mask:0xf bound_ctrl:1
	ds_read_b128 v[100:103], v114 offset:2816
	ds_read_b128 v[96:99], v114 offset:2560
	v_add_f32_dpp v64, v65, v65 quad_perm:[2,3,0,1] row_mask:0xf bank_mask:0xf bound_ctrl:1
	ds_read_b128 v[108:111], v114 offset:3328
	ds_read2st64_b32 v[92:93], v115 offset0:14 offset1:19
	v_add_f32_dpp v65, v64, v64 row_half_mirror row_mask:0xf bank_mask:0xf bound_ctrl:1
	ds_read_b128 v[104:107], v114 offset:3072
	s_nop 0
	v_add_f32_dpp v66, v65, v65 row_mirror row_mask:0xf bank_mask:0xf bound_ctrl:1
	s_waitcnt lgkmcnt(9)
	v_pk_fma_f32 v[2:3], v[48:49], v[66:67], v[60:61] op_sel_hi:[1,0,1]
	v_pk_fma_f32 v[4:5], v[50:51], v[66:67], v[62:63] op_sel_hi:[1,0,1]
	s_waitcnt lgkmcnt(5)
	v_pk_mul_f32 v[58:59], v[80:81], v[2:3]
	v_pk_mul_f32 v[60:61], v[76:77], v[2:3]
	v_pk_fma_f32 v[58:59], v[82:83], v[4:5], v[58:59]
	v_pk_mul_f32 v[62:63], v[78:79], v[4:5]
	v_add_f32_e32 v64, v58, v59
	v_pk_fma_f32 v[60:61], v[88:89], v[56:57], v[60:61] op_sel:[0,1,0]
	v_pk_fma_f32 v[62:63], v[90:91], v[56:57], v[62:63] op_sel:[0,1,0]
	v_add_f32_dpp v65, v64, v64 quad_perm:[1,0,3,2] row_mask:0xf bank_mask:0xf bound_ctrl:1
	v_cvt_pk_bf16_f32 v68, v2, v3
	v_cvt_pk_bf16_f32 v69, v4, v5
	v_add_f32_dpp v64, v65, v65 quad_perm:[2,3,0,1] row_mask:0xf bank_mask:0xf bound_ctrl:1
	ds_write_b64 v116, v[68:69] offset:45056
	ds_read_b128 v[44:47], v114 offset:4096
	v_add_f32_dpp v65, v64, v64 row_half_mirror row_mask:0xf bank_mask:0xf bound_ctrl:1
	ds_read_b128 v[40:43], v114 offset:3840
	ds_read_b128 v[52:55], v114 offset:4608
	v_add_f32_dpp v66, v65, v65 row_mirror row_mask:0xf bank_mask:0xf bound_ctrl:1
	v_pk_fma_f32 v[2:3], v[84:85], v[66:67], v[60:61] op_sel_hi:[1,0,1]
	v_pk_fma_f32 v[4:5], v[86:87], v[66:67], v[62:63] op_sel_hi:[1,0,1]
	ds_read_b128 v[48:51], v114 offset:4352
	s_waitcnt lgkmcnt(5)
	v_pk_mul_f32 v[58:59], v[100:101], v[2:3]
	v_pk_mul_f32 v[60:61], v[96:97], v[2:3]
	v_pk_fma_f32 v[58:59], v[102:103], v[4:5], v[58:59]
	v_pk_mul_f32 v[62:63], v[98:99], v[4:5]
	v_add_f32_e32 v64, v58, v59
	v_pk_fma_f32 v[60:61], v[108:109], v[92:93], v[60:61] op_sel_hi:[1,0,1]
	v_pk_fma_f32 v[62:63], v[110:111], v[92:93], v[62:63] op_sel_hi:[1,0,1]
	v_add_f32_dpp v65, v64, v64 quad_perm:[1,0,3,2] row_mask:0xf bank_mask:0xf bound_ctrl:1
	v_cvt_pk_bf16_f32 v70, v2, v3
	v_cvt_pk_bf16_f32 v71, v4, v5
	v_add_f32_dpp v64, v65, v65 quad_perm:[2,3,0,1] row_mask:0xf bank_mask:0xf bound_ctrl:1
	ds_write_b64 v116, v[70:71] offset:47360
	ds_read_b128 v[80:83], v114 offset:5376
	v_add_f32_dpp v65, v64, v64 row_half_mirror row_mask:0xf bank_mask:0xf bound_ctrl:1
	ds_read_b128 v[76:79], v114 offset:5120
	ds_read_b128 v[88:91], v114 offset:5888
	v_add_f32_dpp v66, v65, v65 row_mirror row_mask:0xf bank_mask:0xf bound_ctrl:1
	v_pk_fma_f32 v[2:3], v[104:105], v[66:67], v[60:61] op_sel_hi:[1,0,1]
	v_pk_fma_f32 v[4:5], v[106:107], v[66:67], v[62:63] op_sel_hi:[1,0,1]
	ds_read2st64_b32 v[56:57], v115 offset0:24 offset1:29
	ds_read_b128 v[84:87], v114 offset:5632
	s_waitcnt lgkmcnt(6)
	v_pk_mul_f32 v[58:59], v[44:45], v[2:3]
	v_pk_mul_f32 v[60:61], v[40:41], v[2:3]
	v_pk_fma_f32 v[58:59], v[46:47], v[4:5], v[58:59]
	v_pk_mul_f32 v[62:63], v[42:43], v[4:5]
	v_add_f32_e32 v64, v58, v59
	v_pk_fma_f32 v[60:61], v[52:53], v[92:93], v[60:61] op_sel:[0,1,0]
	v_pk_fma_f32 v[62:63], v[54:55], v[92:93], v[62:63] op_sel:[0,1,0]
	v_add_f32_dpp v65, v64, v64 quad_perm:[1,0,3,2] row_mask:0xf bank_mask:0xf bound_ctrl:1
	v_cvt_pk_bf16_f32 v68, v2, v3
	v_cvt_pk_bf16_f32 v69, v4, v5
	v_add_f32_dpp v64, v65, v65 quad_perm:[2,3,0,1] row_mask:0xf bank_mask:0xf bound_ctrl:1
	ds_write_b64 v116, v[68:69] offset:49664
	ds_read_b128 v[100:103], v114 offset:6656
	v_add_f32_dpp v65, v64, v64 row_half_mirror row_mask:0xf bank_mask:0xf bound_ctrl:1
	ds_read_b128 v[96:99], v114 offset:6400
	ds_read_b128 v[108:111], v114 offset:7168
	v_add_f32_dpp v66, v65, v65 row_mirror row_mask:0xf bank_mask:0xf bound_ctrl:1
	v_pk_fma_f32 v[2:3], v[48:49], v[66:67], v[60:61] op_sel_hi:[1,0,1]
	v_pk_fma_f32 v[4:5], v[50:51], v[66:67], v[62:63] op_sel_hi:[1,0,1]
	ds_read_b128 v[104:107], v114 offset:6912
	s_waitcnt lgkmcnt(5)
	v_pk_mul_f32 v[58:59], v[80:81], v[2:3]
	v_pk_mul_f32 v[60:61], v[76:77], v[2:3]
	v_pk_fma_f32 v[58:59], v[82:83], v[4:5], v[58:59]
	v_pk_mul_f32 v[62:63], v[78:79], v[4:5]
	v_add_f32_e32 v64, v58, v59
	v_pk_fma_f32 v[60:61], v[88:89], v[56:57], v[60:61] op_sel_hi:[1,0,1]
	v_pk_fma_f32 v[62:63], v[90:91], v[56:57], v[62:63] op_sel_hi:[1,0,1]
	v_add_f32_dpp v65, v64, v64 quad_perm:[1,0,3,2] row_mask:0xf bank_mask:0xf bound_ctrl:1
	v_cvt_pk_bf16_f32 v70, v2, v3
	v_cvt_pk_bf16_f32 v71, v4, v5
	v_add_f32_dpp v64, v65, v65 quad_perm:[2,3,0,1] row_mask:0xf bank_mask:0xf bound_ctrl:1
	ds_write_b64 v116, v[70:71] offset:51968
	ds_read_b128 v[44:47], v114 offset:7936
	v_add_f32_dpp v65, v64, v64 row_half_mirror row_mask:0xf bank_mask:0xf bound_ctrl:1
	ds_read_b128 v[40:43], v114 offset:7680
	ds_read_b128 v[52:55], v114 offset:8448
	v_add_f32_dpp v66, v65, v65 row_mirror row_mask:0xf bank_mask:0xf bound_ctrl:1
	v_pk_fma_f32 v[2:3], v[84:85], v[66:67], v[60:61] op_sel_hi:[1,0,1]
	v_pk_fma_f32 v[4:5], v[86:87], v[66:67], v[62:63] op_sel_hi:[1,0,1]
	ds_read2st64_b32 v[92:93], v115 offset0:34 offset1:39
	ds_read_b128 v[48:51], v114 offset:8192
	s_waitcnt lgkmcnt(6)
	v_pk_mul_f32 v[58:59], v[100:101], v[2:3]
	v_pk_mul_f32 v[60:61], v[96:97], v[2:3]
	v_pk_fma_f32 v[58:59], v[102:103], v[4:5], v[58:59]
	v_pk_mul_f32 v[62:63], v[98:99], v[4:5]
	v_add_f32_e32 v64, v58, v59
	v_pk_fma_f32 v[60:61], v[108:109], v[56:57], v[60:61] op_sel:[0,1,0]
	v_pk_fma_f32 v[62:63], v[110:111], v[56:57], v[62:63] op_sel:[0,1,0]
	v_add_f32_dpp v65, v64, v64 quad_perm:[1,0,3,2] row_mask:0xf bank_mask:0xf bound_ctrl:1
	v_cvt_pk_bf16_f32 v68, v2, v3
	v_cvt_pk_bf16_f32 v69, v4, v5
	v_add_f32_dpp v64, v65, v65 quad_perm:[2,3,0,1] row_mask:0xf bank_mask:0xf bound_ctrl:1
	ds_write_b64 v116, v[68:69] offset:54272
	ds_read_b128 v[80:83], v114 offset:9216
	v_add_f32_dpp v65, v64, v64 row_half_mirror row_mask:0xf bank_mask:0xf bound_ctrl:1
	ds_read_b128 v[76:79], v114 offset:8960
	ds_read_b128 v[88:91], v114 offset:9728
	v_add_f32_dpp v66, v65, v65 row_mirror row_mask:0xf bank_mask:0xf bound_ctrl:1
	v_pk_fma_f32 v[2:3], v[104:105], v[66:67], v[60:61] op_sel_hi:[1,0,1]
	v_pk_fma_f32 v[4:5], v[106:107], v[66:67], v[62:63] op_sel_hi:[1,0,1]
	ds_read_b128 v[84:87], v114 offset:9472
	s_waitcnt lgkmcnt(5)
	v_pk_mul_f32 v[58:59], v[44:45], v[2:3]
	v_pk_mul_f32 v[60:61], v[40:41], v[2:3]
	v_pk_fma_f32 v[58:59], v[46:47], v[4:5], v[58:59]
	v_pk_mul_f32 v[62:63], v[42:43], v[4:5]
	v_add_f32_e32 v64, v58, v59
	v_pk_fma_f32 v[60:61], v[52:53], v[92:93], v[60:61] op_sel_hi:[1,0,1]
	v_pk_fma_f32 v[62:63], v[54:55], v[92:93], v[62:63] op_sel_hi:[1,0,1]
	v_add_f32_dpp v65, v64, v64 quad_perm:[1,0,3,2] row_mask:0xf bank_mask:0xf bound_ctrl:1
	v_cvt_pk_bf16_f32 v70, v2, v3
	v_cvt_pk_bf16_f32 v71, v4, v5
	v_add_f32_dpp v64, v65, v65 quad_perm:[2,3,0,1] row_mask:0xf bank_mask:0xf bound_ctrl:1
	ds_write_b64 v116, v[70:71] offset:56576
	ds_read_b128 v[100:103], v114 offset:10496
	v_add_f32_dpp v65, v64, v64 row_half_mirror row_mask:0xf bank_mask:0xf bound_ctrl:1
	ds_read_b128 v[96:99], v114 offset:10240
	ds_read_b128 v[108:111], v114 offset:11008
	v_add_f32_dpp v66, v65, v65 row_mirror row_mask:0xf bank_mask:0xf bound_ctrl:1
	v_pk_fma_f32 v[2:3], v[48:49], v[66:67], v[60:61] op_sel_hi:[1,0,1]
	v_pk_fma_f32 v[4:5], v[50:51], v[66:67], v[62:63] op_sel_hi:[1,0,1]
	ds_read2st64_b32 v[56:57], v115 offset0:44 offset1:49
	ds_read_b128 v[104:107], v114 offset:10752
	s_waitcnt lgkmcnt(6)
	v_pk_mul_f32 v[58:59], v[80:81], v[2:3]
	v_pk_mul_f32 v[60:61], v[76:77], v[2:3]
	v_pk_fma_f32 v[58:59], v[82:83], v[4:5], v[58:59]
	v_pk_mul_f32 v[62:63], v[78:79], v[4:5]
	v_add_f32_e32 v64, v58, v59
	v_pk_fma_f32 v[60:61], v[88:89], v[92:93], v[60:61] op_sel:[0,1,0]
	v_pk_fma_f32 v[62:63], v[90:91], v[92:93], v[62:63] op_sel:[0,1,0]
	v_add_f32_dpp v65, v64, v64 quad_perm:[1,0,3,2] row_mask:0xf bank_mask:0xf bound_ctrl:1
	v_cvt_pk_bf16_f32 v68, v2, v3
	v_cvt_pk_bf16_f32 v69, v4, v5
	v_add_f32_dpp v64, v65, v65 quad_perm:[2,3,0,1] row_mask:0xf bank_mask:0xf bound_ctrl:1
	ds_write_b64 v116, v[68:69] offset:58880
	ds_read_b128 v[44:47], v114 offset:11776
	v_add_f32_dpp v65, v64, v64 row_half_mirror row_mask:0xf bank_mask:0xf bound_ctrl:1
	ds_read_b128 v[40:43], v114 offset:11520
	ds_read_b128 v[52:55], v114 offset:12288
	v_add_f32_dpp v66, v65, v65 row_mirror row_mask:0xf bank_mask:0xf bound_ctrl:1
	v_pk_fma_f32 v[2:3], v[84:85], v[66:67], v[60:61] op_sel_hi:[1,0,1]
	v_pk_fma_f32 v[4:5], v[86:87], v[66:67], v[62:63] op_sel_hi:[1,0,1]
	ds_read_b128 v[48:51], v114 offset:12032
	s_waitcnt lgkmcnt(5)
	v_pk_mul_f32 v[58:59], v[100:101], v[2:3]
	v_pk_mul_f32 v[60:61], v[96:97], v[2:3]
	v_pk_fma_f32 v[58:59], v[102:103], v[4:5], v[58:59]
	v_pk_mul_f32 v[62:63], v[98:99], v[4:5]
	v_add_f32_e32 v64, v58, v59
	v_pk_fma_f32 v[60:61], v[108:109], v[56:57], v[60:61] op_sel_hi:[1,0,1]
	v_pk_fma_f32 v[62:63], v[110:111], v[56:57], v[62:63] op_sel_hi:[1,0,1]
	v_add_f32_dpp v65, v64, v64 quad_perm:[1,0,3,2] row_mask:0xf bank_mask:0xf bound_ctrl:1
	v_cvt_pk_bf16_f32 v70, v2, v3
	v_cvt_pk_bf16_f32 v71, v4, v5
	v_add_f32_dpp v64, v65, v65 quad_perm:[2,3,0,1] row_mask:0xf bank_mask:0xf bound_ctrl:1
	ds_write_b64 v116, v[70:71] offset:61184
	ds_read_b128 v[80:83], v114 offset:13056
	v_add_f32_dpp v65, v64, v64 row_half_mirror row_mask:0xf bank_mask:0xf bound_ctrl:1
	ds_read_b128 v[76:79], v114 offset:12800
	ds_read_b128 v[88:91], v114 offset:13568
	v_add_f32_dpp v66, v65, v65 row_mirror row_mask:0xf bank_mask:0xf bound_ctrl:1
	v_pk_fma_f32 v[2:3], v[104:105], v[66:67], v[60:61] op_sel_hi:[1,0,1]
	v_pk_fma_f32 v[4:5], v[106:107], v[66:67], v[62:63] op_sel_hi:[1,0,1]
	ds_read2st64_b32 v[92:93], v115 offset0:54 offset1:59
	ds_read_b128 v[84:87], v114 offset:13312
	s_waitcnt lgkmcnt(6)
	v_pk_mul_f32 v[58:59], v[44:45], v[2:3]
	v_pk_mul_f32 v[60:61], v[40:41], v[2:3]
	v_pk_fma_f32 v[58:59], v[46:47], v[4:5], v[58:59]
	v_pk_mul_f32 v[62:63], v[42:43], v[4:5]
	v_add_f32_e32 v64, v58, v59
	v_pk_fma_f32 v[60:61], v[52:53], v[56:57], v[60:61] op_sel:[0,1,0]
	v_pk_fma_f32 v[62:63], v[54:55], v[56:57], v[62:63] op_sel:[0,1,0]
	v_add_f32_dpp v65, v64, v64 quad_perm:[1,0,3,2] row_mask:0xf bank_mask:0xf bound_ctrl:1
	v_cvt_pk_bf16_f32 v68, v2, v3
	v_cvt_pk_bf16_f32 v69, v4, v5
	v_add_f32_dpp v64, v65, v65 quad_perm:[2,3,0,1] row_mask:0xf bank_mask:0xf bound_ctrl:1
	ds_write_b64 v116, v[68:69] offset:63488
	ds_read_b128 v[100:103], v114 offset:14336
	v_add_f32_dpp v65, v64, v64 row_half_mirror row_mask:0xf bank_mask:0xf bound_ctrl:1
	ds_read_b128 v[96:99], v114 offset:14080
	ds_read_b128 v[108:111], v114 offset:14848
	v_add_f32_dpp v66, v65, v65 row_mirror row_mask:0xf bank_mask:0xf bound_ctrl:1
	v_pk_fma_f32 v[2:3], v[48:49], v[66:67], v[60:61] op_sel_hi:[1,0,1]
	v_pk_fma_f32 v[4:5], v[50:51], v[66:67], v[62:63] op_sel_hi:[1,0,1]
	ds_read_b128 v[104:107], v114 offset:14592
	s_waitcnt lgkmcnt(5)
	v_pk_mul_f32 v[58:59], v[80:81], v[2:3]
	v_pk_mul_f32 v[60:61], v[76:77], v[2:3]
	v_pk_fma_f32 v[58:59], v[82:83], v[4:5], v[58:59]
	v_pk_mul_f32 v[62:63], v[78:79], v[4:5]
	v_add_f32_e32 v64, v58, v59
	v_pk_fma_f32 v[60:61], v[88:89], v[92:93], v[60:61] op_sel_hi:[1,0,1]
	v_pk_fma_f32 v[62:63], v[90:91], v[92:93], v[62:63] op_sel_hi:[1,0,1]
	v_add_f32_dpp v65, v64, v64 quad_perm:[1,0,3,2] row_mask:0xf bank_mask:0xf bound_ctrl:1
	v_cvt_pk_bf16_f32 v70, v2, v3
	v_cvt_pk_bf16_f32 v71, v4, v5
	v_add_f32_dpp v64, v65, v65 quad_perm:[2,3,0,1] row_mask:0xf bank_mask:0xf bound_ctrl:1
	ds_write_b64 v117, v[70:71] offset:20736
	ds_read_b128 v[44:47], v114 offset:15616
	v_add_f32_dpp v65, v64, v64 row_half_mirror row_mask:0xf bank_mask:0xf bound_ctrl:1
	ds_read_b128 v[40:43], v114 offset:15360
	ds_read_b128 v[52:55], v114 offset:16128
	v_add_f32_dpp v66, v65, v65 row_mirror row_mask:0xf bank_mask:0xf bound_ctrl:1
	v_pk_fma_f32 v[2:3], v[84:85], v[66:67], v[60:61] op_sel_hi:[1,0,1]
	v_pk_fma_f32 v[4:5], v[86:87], v[66:67], v[62:63] op_sel_hi:[1,0,1]
	ds_read2st64_b32 v[56:57], v115 offset0:64 offset1:69
	ds_read_b128 v[48:51], v114 offset:15872
	s_waitcnt lgkmcnt(6)
	v_pk_mul_f32 v[58:59], v[100:101], v[2:3]
	v_pk_mul_f32 v[60:61], v[96:97], v[2:3]
	v_pk_fma_f32 v[58:59], v[102:103], v[4:5], v[58:59]
	v_pk_mul_f32 v[62:63], v[98:99], v[4:5]
	v_add_f32_e32 v64, v58, v59
	v_pk_fma_f32 v[60:61], v[108:109], v[92:93], v[60:61] op_sel:[0,1,0]
	v_pk_fma_f32 v[62:63], v[110:111], v[92:93], v[62:63] op_sel:[0,1,0]
	v_add_f32_dpp v65, v64, v64 quad_perm:[1,0,3,2] row_mask:0xf bank_mask:0xf bound_ctrl:1
	v_cvt_pk_bf16_f32 v68, v2, v3
	v_cvt_pk_bf16_f32 v69, v4, v5
	v_add_f32_dpp v64, v65, v65 quad_perm:[2,3,0,1] row_mask:0xf bank_mask:0xf bound_ctrl:1
	ds_write_b64 v117, v[68:69] offset:23040
	ds_read_b128 v[80:83], v114 offset:16896
	v_add_f32_dpp v65, v64, v64 row_half_mirror row_mask:0xf bank_mask:0xf bound_ctrl:1
	ds_read_b128 v[76:79], v114 offset:16640
	ds_read_b128 v[88:91], v114 offset:17408
	v_add_f32_dpp v66, v65, v65 row_mirror row_mask:0xf bank_mask:0xf bound_ctrl:1
	v_pk_fma_f32 v[2:3], v[104:105], v[66:67], v[60:61] op_sel_hi:[1,0,1]
	v_pk_fma_f32 v[4:5], v[106:107], v[66:67], v[62:63] op_sel_hi:[1,0,1]
	ds_read_b128 v[84:87], v114 offset:17152
	s_waitcnt lgkmcnt(5)
	v_pk_mul_f32 v[58:59], v[44:45], v[2:3]
	v_pk_mul_f32 v[60:61], v[40:41], v[2:3]
	v_pk_fma_f32 v[58:59], v[46:47], v[4:5], v[58:59]
	v_pk_mul_f32 v[62:63], v[42:43], v[4:5]
	v_add_f32_e32 v64, v58, v59
	v_pk_fma_f32 v[60:61], v[52:53], v[56:57], v[60:61] op_sel_hi:[1,0,1]
	v_pk_fma_f32 v[62:63], v[54:55], v[56:57], v[62:63] op_sel_hi:[1,0,1]
	v_add_f32_dpp v65, v64, v64 quad_perm:[1,0,3,2] row_mask:0xf bank_mask:0xf bound_ctrl:1
	v_cvt_pk_bf16_f32 v70, v2, v3
	v_cvt_pk_bf16_f32 v71, v4, v5
	v_add_f32_dpp v64, v65, v65 quad_perm:[2,3,0,1] row_mask:0xf bank_mask:0xf bound_ctrl:1
	ds_write_b64 v117, v[70:71] offset:25344
	ds_read_b128 v[100:103], v114 offset:18176
	v_add_f32_dpp v65, v64, v64 row_half_mirror row_mask:0xf bank_mask:0xf bound_ctrl:1
	ds_read_b128 v[96:99], v114 offset:17920
	ds_read_b128 v[108:111], v114 offset:18688
	v_add_f32_dpp v66, v65, v65 row_mirror row_mask:0xf bank_mask:0xf bound_ctrl:1
	v_pk_fma_f32 v[2:3], v[48:49], v[66:67], v[60:61] op_sel_hi:[1,0,1]
	v_pk_fma_f32 v[4:5], v[50:51], v[66:67], v[62:63] op_sel_hi:[1,0,1]
	ds_read2st64_b32 v[92:93], v115 offset0:74 offset1:79
	ds_read_b128 v[104:107], v114 offset:18432
	s_waitcnt lgkmcnt(6)
	v_pk_mul_f32 v[58:59], v[80:81], v[2:3]
	v_pk_mul_f32 v[60:61], v[76:77], v[2:3]
	v_pk_fma_f32 v[58:59], v[82:83], v[4:5], v[58:59]
	v_pk_mul_f32 v[62:63], v[78:79], v[4:5]
	v_add_f32_e32 v64, v58, v59
	v_pk_fma_f32 v[60:61], v[88:89], v[56:57], v[60:61] op_sel:[0,1,0]
	v_pk_fma_f32 v[62:63], v[90:91], v[56:57], v[62:63] op_sel:[0,1,0]
	v_add_f32_dpp v65, v64, v64 quad_perm:[1,0,3,2] row_mask:0xf bank_mask:0xf bound_ctrl:1
	v_cvt_pk_bf16_f32 v68, v2, v3
	v_cvt_pk_bf16_f32 v69, v4, v5
	v_add_f32_dpp v64, v65, v65 quad_perm:[2,3,0,1] row_mask:0xf bank_mask:0xf bound_ctrl:1
	ds_write_b64 v117, v[68:69] offset:27648
	ds_read_b128 v[44:47], v114 offset:19456
	v_add_f32_dpp v65, v64, v64 row_half_mirror row_mask:0xf bank_mask:0xf bound_ctrl:1
	ds_read_b128 v[40:43], v114 offset:19200
	ds_read_b128 v[52:55], v114 offset:19968
	v_add_f32_dpp v66, v65, v65 row_mirror row_mask:0xf bank_mask:0xf bound_ctrl:1
	v_pk_fma_f32 v[2:3], v[84:85], v[66:67], v[60:61] op_sel_hi:[1,0,1]
	v_pk_fma_f32 v[4:5], v[86:87], v[66:67], v[62:63] op_sel_hi:[1,0,1]
	ds_read_b128 v[48:51], v114 offset:19712
	s_waitcnt lgkmcnt(5)
	v_pk_mul_f32 v[58:59], v[100:101], v[2:3]
	v_pk_mul_f32 v[60:61], v[96:97], v[2:3]
	v_pk_fma_f32 v[58:59], v[102:103], v[4:5], v[58:59]
	v_pk_mul_f32 v[62:63], v[98:99], v[4:5]
	v_add_f32_e32 v64, v58, v59
	v_pk_fma_f32 v[60:61], v[108:109], v[92:93], v[60:61] op_sel_hi:[1,0,1]
	v_pk_fma_f32 v[62:63], v[110:111], v[92:93], v[62:63] op_sel_hi:[1,0,1]
	v_add_f32_dpp v65, v64, v64 quad_perm:[1,0,3,2] row_mask:0xf bank_mask:0xf bound_ctrl:1
	v_cvt_pk_bf16_f32 v70, v2, v3
	v_cvt_pk_bf16_f32 v71, v4, v5
	v_add_f32_dpp v64, v65, v65 quad_perm:[2,3,0,1] row_mask:0xf bank_mask:0xf bound_ctrl:1
	ds_write_b64 v117, v[70:71] offset:29952
	s_nop 0
	v_add_f32_dpp v65, v64, v64 row_half_mirror row_mask:0xf bank_mask:0xf bound_ctrl:1
	s_nop 0
	s_nop 0
	v_add_f32_dpp v66, v65, v65 row_mirror row_mask:0xf bank_mask:0xf bound_ctrl:1
	v_pk_fma_f32 v[2:3], v[104:105], v[66:67], v[60:61] op_sel_hi:[1,0,1]
	v_pk_fma_f32 v[4:5], v[106:107], v[66:67], v[62:63] op_sel_hi:[1,0,1]
	s_waitcnt lgkmcnt(1)
	v_pk_mul_f32 v[58:59], v[44:45], v[2:3]
	v_pk_mul_f32 v[60:61], v[40:41], v[2:3]
	v_pk_fma_f32 v[58:59], v[46:47], v[4:5], v[58:59]
	v_pk_mul_f32 v[62:63], v[42:43], v[4:5]
	v_add_f32_e32 v64, v58, v59
	v_pk_fma_f32 v[60:61], v[52:53], v[92:93], v[60:61] op_sel:[0,1,0]
	v_pk_fma_f32 v[62:63], v[54:55], v[92:93], v[62:63] op_sel:[0,1,0]
	v_add_f32_dpp v65, v64, v64 quad_perm:[1,0,3,2] row_mask:0xf bank_mask:0xf bound_ctrl:1
	v_cvt_pk_bf16_f32 v68, v2, v3
	v_cvt_pk_bf16_f32 v69, v4, v5
	v_add_f32_dpp v64, v65, v65 quad_perm:[2,3,0,1] row_mask:0xf bank_mask:0xf bound_ctrl:1
	ds_write_b64 v117, v[68:69] offset:32256
	s_nop 0
	v_add_f32_dpp v65, v64, v64 row_half_mirror row_mask:0xf bank_mask:0xf bound_ctrl:1
	s_nop 0
	s_nop 0
	v_add_f32_dpp v66, v65, v65 row_mirror row_mask:0xf bank_mask:0xf bound_ctrl:1
	v_pk_fma_f32 v[2:3], v[48:49], v[66:67], v[60:61] op_sel_hi:[1,0,1]
	v_pk_fma_f32 v[4:5], v[50:51], v[66:67], v[62:63] op_sel_hi:[1,0,1]
	v_cvt_pk_bf16_f32 v70, v2, v3
	v_cvt_pk_bf16_f32 v71, v4, v5
	ds_write_b64 v117, v[70:71] offset:34560
	s_add_i32 s0, s0, 1
	s_waitcnt lgkmcnt(0)
	s_barrier
	s_branch .LBB0_1047
.Lscan_done:
	s_setprio 0
	s_mov_b64 s[0:1], 0
